# k34: k33 + attention prologue requests Q before the register-staged K/V tiles and enters the tile loop with the last two tiles still in flight (loop wait count 5)
# speedup vs baseline: 1.0176x; 1.0135x over previous
; #define LAS __attribute__((address_space(3)))
; #define ATT_GLD16(dst, ptr) asm volatile("global_load_dwordx4 %0, %1, off" : "=&v"(dst) : "v"(ptr) : "memory")
; __device__ __forceinline__ void attn_unit(const UnitDesc& u, LAS unsigned char* shm, float qkmax, float thresh) {
;     ...
;     const bf16_t* ksrc = u.K + (size_t)lane * 512 + wid * 8;
;     const bf16_t* vsrc = u.V + (size_t)(16 * (wid & 3) + (lane >> 2)) * 512 + (wid >> 2) * 32 + (lane & 3) * 8;
;     const float* lsrc = u.LF + (size_t)lane * 8;
;     LAS unsigned char* kdst = shm + LDS_K + wid * 1024 + lane * 16;
;     LAS unsigned char* vdst = shm + LDS_V + wid * 1024 + lane * 16;
;     const int vb0 = (int)(unsigned)(uintptr_t)(shm + LDS_V) + ((lane >> 4) & 1) * 32 + (lane & 3) * 8 + (4 * hi + ((lane & 15) >> 2)) * 64;
;     const LAS unsigned char* kb = shm + LDS_K + hi * 1024 + r32 * 16;
;     ...
;     u32x4 kreg = *(const u32x4*)(ksrc + (size_t)(NT - 1) * 64 * 512), vreg = *(const u32x4*)(vsrc + (size_t)(NT - 1) * 64 * 512);
;     float lfb[4];
; #pragma unroll
;     for (int jb = 0; jb < 4; ++jb) { const int tile = NT - 1 - jb; lfb[jb] = lsrc[(size_t)(tile > 0 ? tile : 0) * 64 * 8]; }
;     u32x4 kA, vA, kB, vB, kC, vC;
;     { const int t2 = NT >= 2 ? NT - 2 : 0, t3 = NT >= 3 ? NT - 3 : 0, t4 = NT >= 4 ? NT - 4 : 0;
;       ATT_GLD16(kA, ksrc + (size_t)t2 * 64 * 512); ATT_GLD16(vA, vsrc + (size_t)t2 * 64 * 512);
;       ATT_GLD16(kB, ksrc + (size_t)t3 * 64 * 512); ATT_GLD16(vB, vsrc + (size_t)t3 * 64 * 512);
;       ATT_GLD16(kC, ksrc + (size_t)t4 * 64 * 512); ATT_GLD16(vC, vsrc + (size_t)t4 * 64 * 512); }
;     bf16x8 qr[4];
; #pragma unroll
;     for (int d0 = 0; d0 < 4; ++d0) qr[d0] = (bf16x8){0, 0, 0, 0, 0, 0, 0, 0};
;     if (active) { const bf16_t* Qw = u.Q + (size_t)(wid * 32 + r32) * 512;
; #pragma unroll
;         for (int d0 = 0; d0 < 4; ++d0) qr[d0] = *(const bf16x8*)(Qw + d0 * 16 + hi * 8); }
.LBB0_731:
	s_lshl_b64 s[48:49], s[28:29], 2
	v_mov_b32_e32 v12, v208
	s_add_u32 s12, s12, s48
	s_addc_u32 s13, s13, s49
	v_and_b32_e32 v137, 63, v12
	v_readfirstlane_b32 s68, v12
	s_ashr_i32 s52, s68, 6
	v_lshlrev_b32_e32 v0, 10, v137
	v_lshl_add_u64 v[2:3], s[10:11], 0, v[0:1]
	s_lshl_b32 s10, s52, 3
	s_ashr_i32 s11, s10, 31
	v_lshl_add_u64 v[106:107], s[10:11], 1, v[2:3]
	s_lshl_b32 s10, s52, 4
	v_bfe_u32 v0, v12, 2, 4
	v_and_or_b32 v0, s10, 48, v0
	v_lshlrev_b32_e32 v0, 10, v0
	s_add_i32 s28, s53, s66
	v_lshl_add_u64 v[2:3], s[8:9], 0, v[0:1]
	s_ashr_i32 s8, s68, 3
	s_ashr_i32 s67, s28, 6
	s_andn2_b32 s8, s8, 31
	v_lshlrev_b32_e32 v138, 3, v12
	s_ashr_i32 s9, s8, 31
	v_and_b32_e32 v13, 24, v138
	s_add_i32 s48, s67, -1
	v_lshl_add_u64 v[2:3], s[8:9], 1, v[2:3]
	v_lshlrev_b32_e32 v0, 1, v13
	s_ashr_i32 s49, s48, 31
	v_lshl_add_u64 v[108:109], v[2:3], 0, v[0:1]
	v_lshlrev_b32_e32 v0, 5, v137
	s_lshl_b64 s[8:9], s[48:49], 16
	s_max_i32 s28, s48, 0
	v_lshl_add_u64 v[110:111], s[12:13], 0, v[0:1]
	v_lshl_add_u64 v[2:3], v[106:107], 0, s[8:9]
	v_lshl_add_u64 v[6:7], v[108:109], 0, s[8:9]
	s_lshl_b64 s[8:9], s[28:29], 11
	v_lshl_add_u64 v[10:11], v[110:111], 0, s[8:9]
	s_max_i32 s8, s67, 2
	s_add_i32 s28, s8, -2
	s_lshl_b64 s[8:9], s[28:29], 11
	v_lshl_add_u64 v[16:17], v[110:111], 0, s[8:9]
	s_max_i32 s8, s67, 3
	s_add_i32 s8, s8, -3
	s_mov_b32 s9, s29
	s_lshl_b64 s[10:11], s[8:9], 11
	v_lshl_add_u64 v[18:19], v[110:111], 0, s[10:11]
	s_max_i32 s10, s67, 4
	s_add_i32 s10, s10, -4
	s_mov_b32 s11, s29
	s_lshl_b64 s[12:13], s[10:11], 11
	global_load_dwordx4 v[2:5], v[2:3], off
	v_lshl_add_u64 v[20:21], v[110:111], 0, s[12:13]
	global_load_dwordx4 v[6:9], v[6:7], off
	s_nop 0
	global_load_dword v14, v[10:11], off
	global_load_dword v140, v[16:17], off
	global_load_dword v141, v[18:19], off
	global_load_dword v139, v[20:21], off
	s_lshl_b32 s49, s52, 5
	s_cmp_lt_i32 s49, s53
	s_cselect_b64 s[58:59], -1, 0
	s_cmp_ge_i32 s49, s53
	s_cselect_b64 s[60:61], -1, 0
	v_and_b32_e32 v135, 31, v12
	v_bfe_u32 v136, v12, 5, 1
	s_and_b64 vcc, exec, s[60:61]
	v_or_b32_e32 v10, s49, v135
	s_cbranch_vccnz .LBB0_733
	v_ashrrev_i32_e32 v11, 31, v10
	v_lshlrev_b64 v[16:17], 10, v[10:11]
	v_lshl_add_u64 v[16:17], s[6:7], 0, v[16:17]
	v_lshlrev_b32_e32 v0, 4, v136
	v_lshl_add_u64 v[16:17], v[16:17], 0, v[0:1]
	global_load_dwordx4 v[94:97], v[16:17], off
	global_load_dwordx4 v[98:101], v[16:17], off offset:32
	global_load_dwordx4 v[102:105], v[16:17], off offset:64
	global_load_dwordx4 v[90:93], v[16:17], off offset:96
	s_branch .LBB0_734

; #define DPP_SHL(v, n) __builtin_bit_cast(float, __builtin_amdgcn_update_dpp(0, __builtin_bit_cast(int, (v)), 0x100 | (n), 0xF, 0xF, true))
; #define ATT_GLD16(dst, ptr) asm volatile("global_load_dwordx4 %0, %1, off" : "=&v"(dst) : "v"(ptr) : "memory")
; __device__ __forceinline__ float suffix_incl(float v, int lane) {
;     v += DPP_SHL(v, 1); v += DPP_SHL(v, 2); v += DPP_SHL(v, 4); v += DPP_SHL(v, 8);
;     const float t1 = __builtin_bit_cast(float, __builtin_amdgcn_readlane(__builtin_bit_cast(int, v), 16)), t2 = __builtin_bit_cast(float, __builtin_amdgcn_readlane(__builtin_bit_cast(int, v), 32)),
;                 t3 = __builtin_bit_cast(float, __builtin_amdgcn_readlane(__builtin_bit_cast(int, v), 48));
;     const int row = lane >> 4;
;     const float add = (row == 0) ? (t1 + t2) + t3 : (row == 1) ? t2 + t3 : (row == 2) ? t3 : 0.f;
;     return v + add;
; }
; __device__ __forceinline__ void attn_unit(const UnitDesc& u, LAS unsigned char* shm, float qkmax, float thresh) {
;     ...
;     { const int t2 = NT >= 2 ? NT - 2 : 0, t3 = NT >= 3 ? NT - 3 : 0, t4 = NT >= 4 ? NT - 4 : 0;
;       ATT_GLD16(kA, ksrc + (size_t)t2 * 64 * 512); ATT_GLD16(vA, vsrc + (size_t)t2 * 64 * 512);
;       ATT_GLD16(kB, ksrc + (size_t)t3 * 64 * 512); ATT_GLD16(vB, vsrc + (size_t)t3 * 64 * 512);
;       ATT_GLD16(kC, ksrc + (size_t)t4 * 64 * 512); ATT_GLD16(vC, vsrc + (size_t)t4 * 64 * 512); }
.LBB0_734:
	s_lshl_b64 s[12:13], s[28:29], 16
	v_lshl_add_u64 v[188:189], v[106:107], 0, s[12:13]
	global_load_dwordx4 v[66:69], v[188:189], off
	v_lshl_add_u64 v[188:189], v[108:109], 0, s[12:13]
	global_load_dwordx4 v[74:77], v[188:189], off
	s_lshl_b64 s[8:9], s[8:9], 16
	v_lshl_add_u64 v[188:189], v[106:107], 0, s[8:9]
	global_load_dwordx4 v[70:73], v[188:189], off
	v_lshl_add_u64 v[188:189], v[108:109], 0, s[8:9]
	global_load_dwordx4 v[82:85], v[188:189], off
	s_lshl_b64 s[8:9], s[10:11], 16
	v_lshl_add_u64 v[188:189], v[106:107], 0, s[8:9]
	global_load_dwordx4 v[78:81], v[188:189], off
	v_lshl_add_u64 v[188:189], v[108:109], 0, s[8:9]
	global_load_dwordx4 v[86:89], v[188:189], off
	v_lshrrev_b32_e32 v0, 4, v137
	v_cmp_ne_u32_e64 s[8:9], 1, v0
	v_cmp_eq_u32_e64 s[10:11], 2, v0
	s_waitcnt vmcnt(9)
	v_add_f32_dpp v0, v14, v14 row_shl:1 row_mask:0xf bank_mask:0xf bound_ctrl:1
	v_cmp_lt_u32_e64 s[6:7], 15, v137
	s_nop 0
	v_add_f32_dpp v0, v0, v0 row_shl:2 row_mask:0xf bank_mask:0xf bound_ctrl:1
	s_nop 1
	v_add_f32_dpp v0, v0, v0 row_shl:4 row_mask:0xf bank_mask:0xf bound_ctrl:1
	s_nop 1
	v_add_f32_dpp v0, v0, v0 row_shl:8 row_mask:0xf bank_mask:0xf bound_ctrl:1
	s_nop 0
	v_readlane_b32 s28, v0, 16
	v_readlane_b32 s70, v0, 32
	v_readlane_b32 s69, v0, 48
	s_and_saveexec_b64 s[12:13], s[6:7]
	s_xor_b64 s[12:13], exec, s[12:13]
	s_cbranch_execz .LBB0_740
	s_and_saveexec_b64 s[64:65], s[8:9]
	s_xor_b64 s[64:65], exec, s[64:65]
	v_mov_b32_e32 v11, s69
	v_cndmask_b32_e64 v11, 0, v11, s[10:11]
	s_andn2_saveexec_b64 s[64:65], s[64:65]
	v_mov_b32_e32 v11, s69
	v_add_f32_e32 v11, s70, v11
	s_or_b64 exec, exec, s[64:65]

; #define LAS __attribute__((address_space(3)))
; __device__ __forceinline__ float lane0(float v) { return __builtin_bit_cast(float, __builtin_amdgcn_readfirstlane(__builtin_bit_cast(int, v))); }
; __device__ __forceinline__ void attn_unit(const UnitDesc& u, LAS unsigned char* shm, float qkmax, float thresh) {
;     ...
;     const float ci = -Rown * LOG2E - qkmax;
;     const float kbq0 = Rq0 * LOG2E;
;     const int qabs = u.q0 + wid * 32 + r32;
;     float l_reg = 0.f; f32x16 o[2]; o[0] = f32x16{}; o[1] = f32x16{};
;     float lA = lfb[1], lB = lfb[2], lC = lfb[3];
;     { const float lf = lfb[0]; const float inc = inc4[0]; wsf[lane] = (inc - lf) * LOG2E; carry = lane0(inc);
;       *(LAS u32x4*)kdst = kreg; *(LAS u32x4*)vdst = vreg;
;       asm volatile("" : "+v"(qr[0]), "+v"(qr[1]), "+v"(qr[2]), "+v"(qr[3]));
;       asm volatile("s_waitcnt vmcnt(0)" : "+v"(kA), "+v"(vA), "+v"(kB), "+v"(vB), "+v"(kC), "+v"(vC) :: "memory"); }
;     int slot = 0, tile = NT - 1; bool stop = false;
.LBB0_772:
	v_lshlrev_b32_e32 v15, 1, v12
	s_lshl_b32 s12, s52, 10
	v_and_b32_e32 v15, 32, v15
	s_add_i32 s13, 0, 0x2000
	v_lshlrev_b32_e32 v142, 2, v136
	v_lshrrev_b32_e32 v12, 2, v12
	s_add_i32 s12, s12, 0
	v_add_u32_e32 v15, s13, v15
	v_and_or_b32 v12, v12, 3, v142
	s_lshl_b32 s13, s52, 9
	v_lshlrev_b32_e32 v12, 6, v12
	s_sub_i32 s53, s12, s13
	v_add_u32_e32 v147, s66, v10
	v_sub_f32_e32 v10, v0, v14
	v_lshl_add_u32 v143, v137, 4, s12
	v_add3_u32 v144, v15, v13, v12
	s_mov_b32 s12, 0xbfb8aa3b
	s_waitcnt lgkmcnt(0)
	v_mul_f32_e32 v146, 0x3fb8aa3b, v11
	v_mul_f32_e32 v10, 0x3fb8aa3b, v10
	v_lshl_add_u32 v11, v137, 2, s53
	v_mov_b32_e32 v14, v1
	v_mov_b32_e32 v15, v1
	v_lshlrev_b32_e32 v16, 10, v136
	v_lshlrev_b32_e32 v17, 4, v135
	v_fma_f32 v112, v21, s12, -v130
	v_mul_f32_e32 v197, 0x3fb8aa3b, v21
	s_mov_b64 s[98:99], 0
	s_nop 0
	v_readfirstlane_b32 s100, v197
	s_nop 3
	v_mov_b32_e32 v197, s100
	ds_write_b32 v11, v10 offset:32768
	v_readfirstlane_b32 s12, v0
	ds_write_b128 v143, v[2:5]
	ds_write_b128 v143, v[6:9] offset:8192
	v_mov_b32_e32 v0, v1
	v_mov_b32_e32 v2, v1
	v_mov_b32_e32 v3, v1
	v_mov_b32_e32 v4, v1
	v_mov_b32_e32 v5, v1
	v_mov_b32_e32 v6, v1
	v_mov_b32_e32 v7, v1
	v_mov_b32_e32 v8, v1
	v_mov_b32_e32 v9, v1
	v_mov_b32_e32 v10, v1
	v_mov_b32_e32 v11, v1
	v_mov_b32_e32 v12, v1
	v_mov_b32_e32 v13, v1
	v_mov_b64_e32 v[48:49], v[14:15]
	v_mov_b64_e32 v[64:65], v[14:15]
	v_mov_b64_e32 v[32:33], v[14:15]
	v_add3_u32 v145, 0, v16, v17
	s_add_i32 s73, s66, s49
	v_mov_b64_e32 v[46:47], v[12:13]
	v_mov_b64_e32 v[44:45], v[10:11]
	v_mov_b64_e32 v[42:43], v[8:9]
	v_mov_b64_e32 v[40:41], v[6:7]
	v_mov_b64_e32 v[38:39], v[4:5]
	v_mov_b64_e32 v[36:37], v[2:3]
	v_mov_b64_e32 v[34:35], v[0:1]
	v_mov_b64_e32 v[62:63], v[12:13]
	v_mov_b64_e32 v[60:61], v[10:11]
	v_mov_b64_e32 v[58:59], v[8:9]
	v_mov_b64_e32 v[56:57], v[6:7]
	v_mov_b64_e32 v[54:55], v[4:5]
	v_mov_b64_e32 v[52:53], v[2:3]
	v_mov_b64_e32 v[50:51], v[0:1]
	v_mov_b64_e32 v[30:31], v[12:13]
	v_mov_b64_e32 v[28:29], v[10:11]
	v_mov_b64_e32 v[26:27], v[8:9]
	v_mov_b64_e32 v[24:25], v[6:7]
	v_mov_b64_e32 v[22:23], v[4:5]
	v_mov_b64_e32 v[20:21], v[2:3]
	v_mov_b64_e32 v[18:19], v[0:1]
	v_mov_b64_e32 v[16:17], v[14:15]
	s_sub_i32 s72, s67, s28
	s_add_i32 s73, s73, 31
	v_mov_b32_e32 v113, v112
	v_mov_b32_e32 v114, v112
	v_mov_b32_e32 v115, v112
	v_mov_b32_e32 v116, v112
	v_mov_b32_e32 v117, v112
	v_mov_b32_e32 v118, v112
	v_mov_b32_e32 v119, v112
	v_mov_b32_e32 v120, v112
	v_mov_b32_e32 v121, v112
	v_mov_b32_e32 v122, v112
	v_mov_b32_e32 v123, v112
	v_mov_b32_e32 v124, v112
	v_mov_b32_e32 v125, v112
	v_mov_b32_e32 v126, v112
	v_mov_b32_e32 v127, v112
	s_lshl_b32 s75, s67, 6
	s_mov_b32 s70, 0
	v_mov_b32_e32 v148, 0
	s_mov_b64 s[62:63], 0
	v_mov_b32_e32 v150, s12
	v_mov_b64_e32 v[14:15], v[12:13]
	v_mov_b64_e32 v[12:13], v[10:11]
	v_mov_b64_e32 v[10:11], v[8:9]
	v_mov_b64_e32 v[8:9], v[6:7]
	v_mov_b64_e32 v[6:7], v[4:5]
	v_mov_b64_e32 v[4:5], v[2:3]
	v_mov_b64_e32 v[2:3], v[0:1]
	s_waitcnt vmcnt(4)
	s_branch .LBB0_777

.LBB0_777:
	s_waitcnt lgkmcnt(0)
	s_barrier
	s_waitcnt vmcnt(5)
	s_nop 1
	v_add_f32_dpp v0, v140, v140 row_shl:1 row_mask:0xf bank_mask:0xf bound_ctrl:1
	s_nop 1
	v_add_f32_dpp v0, v0, v0 row_shl:2 row_mask:0xf bank_mask:0xf bound_ctrl:1
	s_nop 1
	v_add_f32_dpp v0, v0, v0 row_shl:4 row_mask:0xf bank_mask:0xf bound_ctrl:1
	s_nop 1
	v_add_f32_dpp v0, v0, v0 row_shl:8 row_mask:0xf bank_mask:0xf bound_ctrl:1
	s_nop 0
	v_readlane_b32 s28, v0, 16
	v_readlane_b32 s67, v0, 32
	v_readlane_b32 s66, v0, 48
	s_and_saveexec_b64 s[12:13], s[6:7]
	s_xor_b64 s[12:13], exec, s[12:13]
	s_cbranch_execz .LBB0_783
	s_and_saveexec_b64 s[64:65], s[8:9]
	s_xor_b64 s[64:65], exec, s[64:65]
	v_mov_b32_e32 v149, s66
	v_cndmask_b32_e64 v149, 0, v149, s[10:11]
	s_andn2_saveexec_b64 s[64:65], s[64:65]
	v_mov_b32_e32 v149, s66
	v_add_f32_e32 v149, s67, v149
	s_or_b64 exec, exec, s[64:65]

; __device__ __forceinline__ void attn_unit(const UnitDesc& u, LAS unsigned char* shm, float qkmax, float thresh) {
;     ...
;     for (;;) {
;         ATT_ITER(kA, vA, lA); if (stop) break;
;         ATT_ITER(kB, vB, lB); if (stop) break;
.LBB0_792:
	s_cmp_lg_u32 s48, 0
	v_fma_f32 v151, v150, s50, -v146
	s_cselect_b64 s[64:65], -1, 0
	v_cmp_nlt_f32_e64 s[66:67], v151, -v131
	v_fma_f32 v196, v150, s50, -v197
	v_cmp_lt_f32_e64 s[100:101], v196, -v131
	s_nop 3
	s_or_b64 s[98:99], s[98:99], s[100:101]
	s_and_b64 s[68:69], s[64:65], s[66:67]
	s_mov_b64 s[66:67], -1
	s_and_saveexec_b64 s[64:65], s[68:69]
	s_cbranch_execz .LBB0_776
	s_waitcnt lgkmcnt(0)
	s_barrier
	s_waitcnt vmcnt(5)
	s_nop 1
	v_add_f32_dpp v151, v141, v141 row_shl:1 row_mask:0xf bank_mask:0xf bound_ctrl:1
	s_nop 1
	v_add_f32_dpp v151, v151, v151 row_shl:2 row_mask:0xf bank_mask:0xf bound_ctrl:1
	s_nop 1
	v_add_f32_dpp v151, v151, v151 row_shl:4 row_mask:0xf bank_mask:0xf bound_ctrl:1
	s_nop 1
	v_add_f32_dpp v152, v151, v151 row_shl:8 row_mask:0xf bank_mask:0xf bound_ctrl:1
	s_nop 0
	v_readlane_b32 s28, v152, 16
	v_readlane_b32 s79, v152, 32
	v_readlane_b32 s77, v152, 48
	s_and_saveexec_b64 s[66:67], s[6:7]
	s_xor_b64 s[66:67], exec, s[66:67]
	s_cbranch_execz .LBB0_799
	s_and_saveexec_b64 s[68:69], s[8:9]
	s_xor_b64 s[68:69], exec, s[68:69]
	v_mov_b32_e32 v151, s77
	v_cndmask_b32_e64 v153, 0, v151, s[10:11]
	s_andn2_saveexec_b64 s[68:69], s[68:69]
	v_mov_b32_e32 v151, s77
	v_add_f32_e32 v153, s79, v151
	s_or_b64 exec, exec, s[68:69]

; __device__ __forceinline__ void attn_unit(const UnitDesc& u, LAS unsigned char* shm, float qkmax, float thresh) {
;     ...
;     for (;;) {
;         ATT_ITER(kA, vA, lA); if (stop) break;
;         ATT_ITER(kB, vB, lB); if (stop) break;
;         ATT_ITER(kC, vC, lC); if (stop) break;
.LBB0_808:
	s_cmp_lg_u32 s48, 1
	v_fma_f32 v150, v151, s50, -v146
	s_cselect_b64 s[66:67], -1, 0
	v_cmp_nlt_f32_e64 s[68:69], v150, -v131
	v_fma_f32 v196, v151, s50, -v197
	v_cmp_lt_f32_e64 s[100:101], v196, -v131
	s_nop 3
	s_or_b64 s[98:99], s[98:99], s[100:101]
	s_and_b64 s[70:71], s[66:67], s[68:69]
	s_mov_b64 s[68:69], -1
	s_and_saveexec_b64 s[66:67], s[70:71]
	s_cbranch_execz .LBB0_775
	s_waitcnt lgkmcnt(0)
	s_barrier
	s_waitcnt vmcnt(5)
	s_nop 1
	v_add_f32_dpp v150, v139, v139 row_shl:1 row_mask:0xf bank_mask:0xf bound_ctrl:1
	s_nop 1
	v_add_f32_dpp v150, v150, v150 row_shl:2 row_mask:0xf bank_mask:0xf bound_ctrl:1
	s_nop 1
	v_add_f32_dpp v150, v150, v150 row_shl:4 row_mask:0xf bank_mask:0xf bound_ctrl:1
	s_nop 1
	v_add_f32_dpp v150, v150, v150 row_shl:8 row_mask:0xf bank_mask:0xf bound_ctrl:1
	s_nop 0
	v_readlane_b32 s28, v150, 16
	v_readlane_b32 s80, v150, 32
	v_readlane_b32 s78, v150, 48
	s_and_saveexec_b64 s[68:69], s[6:7]
	s_xor_b64 s[68:69], exec, s[68:69]
	s_cbranch_execz .LBB0_815
	s_and_saveexec_b64 s[70:71], s[8:9]
	s_xor_b64 s[70:71], exec, s[70:71]
	v_mov_b32_e32 v152, s78
	v_cndmask_b32_e64 v152, 0, v152, s[10:11]
	s_andn2_saveexec_b64 s[70:71], s[70:71]
	v_mov_b32_e32 v152, s78
	v_add_f32_e32 v152, s80, v152
	s_or_b64 exec, exec, s[70:71]
